# attn1 tiles>=1: lazy softmax rescale checked on row sum after exp (power-of-two rescale), no per-tile max in hot path; tile 0 keeps max-based path
# speedup vs baseline: 1.0334x; 1.0182x over previous
; #define LAS __attribute__((address_space(3)))
; template <int DQ, bool BIAS, bool TAIL>
; __device__ __forceinline__ void attn_item(const AttnItem& A, LAS unsigned char* lds, int wave_s_) {
;     ...
;         if (act) {
; #pragma unroll
;             for (int kk = 0; kk < NKK; ++kk) kf[kk] = *(const LAS bf16x8*)(kb + (16 * kk) * 2);
;         }
;         if (more) ATT_GLOAD(t + 1);
;         if (act) {
; #pragma unroll
;             for (int kbk = 0; kbk < 2; ++kbk) {
;                 __builtin_amdgcn_sched_barrier(0);
;                 f32x16 s[2];
;                 s[0] = MFMA32(kf[0], qf[0][0], zero16v); s[1] = MFMA32(kf[0], qf[1][0], zero16v);
; #pragma unroll
;                 for (int kk = 1; kk < NKK; ++kk) { s[0] = MFMA32(kf[kk], qf[0][kk], s[0]); s[1] = MFMA32(kf[kk], qf[1][kk], s[1]); }
;                 s16x4 vlo[2][2], vhi[2][2];
; #pragma unroll
;                 for (int st = 0; st < 2; ++st)
; #pragma unroll
;                     for (int d = 0; d < 2; ++d) { const LAS unsigned char* vp = vb + ((32 * kbk + 16 * st) * VROW + 32 * d) * 2; vlo[st][d] = vtr(vp); vhi[st][d] = vtr(vp + 8 * VROW * 2); }
;                 __builtin_amdgcn_sched_barrier(0);
;                 float mx[2];
; #pragma unroll
;                 for (int qb = 0; qb < 2; ++qb) {
;                     if (BIAS || TAIL) {
;                         const int qk = A.q_kidx0 + 64 * w + 32 * qb + r32;
; #pragma unroll
;                         for (int i = 0; i < 16; ++i) { const int kidx = 64 * t + 32 * kbk + crow(i, hi);
;                             float v = s[qb][i]; if (BIAS) v += lut[kidx - qk + LUT0]; if (TAIL && kidx >= A.nkeys) v = -1.0e30f; s[qb][i] = v; }
;                     }
;                     const float t0 = max3f(s[qb][0], s[qb][1], s[qb][2]), t1 = max3f(s[qb][3], s[qb][4], s[qb][5]), t2 = max3f(s[qb][6], s[qb][7], s[qb][8]),
;                                 t3 = max3f(s[qb][9], s[qb][10], s[qb][11]), t4 = max3f(s[qb][12], s[qb][13], s[qb][14]);
;                     const float m = max3f(max3f(t0, t1, t2), max3f(t3, t4, s[qb][15]), t0);
;                     mx[qb] = swapmax(m, hi) - mref[qb];
;                 }
;                 const bool need0 = first || mx[0] > RESCALE_THR, need1 = first || mx[1] > RESCALE_THR;
;                 if (__builtin_amdgcn_ballot_w64(need0 || need1) != 0ull) {
.LBB0_1478:
	s_or_b64 exec, exec, s[10:11]
	s_andn2_b64 vcc, exec, s[8:9]
	s_cbranch_vccnz .LBB0_1484
	s_cmp_lg_u32 s22, 0
	s_cbranch_scc1 .Lp6_body
	s_mul_i32 s8, s21, 0x2400
	v_add_u32_e32 v229, s8, v227
	s_waitcnt lgkmcnt(5)
	v_mfma_f32_32x32x16_bf16 v[80:95], v[176:179], v[96:99], 0
	ds_read_b64_tr_b16 v[192:193], v229 offset:26624
	ds_read_b64_tr_b16 v[194:195], v229 offset:27776
	ds_read_b64_tr_b16 v[188:189], v229 offset:26688
	ds_read_b64_tr_b16 v[190:191], v229 offset:27840
	ds_read_b64_tr_b16 v[184:185], v229 offset:28928
	ds_read_b64_tr_b16 v[186:187], v229 offset:30080
	ds_read_b64_tr_b16 v[180:181], v229 offset:28992
	ds_read_b64_tr_b16 v[182:183], v229 offset:30144
	s_waitcnt lgkmcnt(12)
	v_mfma_f32_32x32x16_bf16 v[80:95], v[172:175], v[100:103], v[80:95]
	s_waitcnt lgkmcnt(11)
	v_mfma_f32_32x32x16_bf16 v[80:95], v[168:171], v[104:107], v[80:95]
	s_waitcnt lgkmcnt(10)
	v_mfma_f32_32x32x16_bf16 v[80:95], v[164:167], v[108:111], v[80:95]
	s_waitcnt lgkmcnt(9)
	v_mfma_f32_32x32x16_bf16 v[80:95], v[160:163], v[112:115], v[80:95]
	s_waitcnt lgkmcnt(8)
	v_mfma_f32_32x32x16_bf16 v[80:95], v[156:159], v[116:119], v[80:95]
	v_mfma_f32_32x32x16_bf16 v[64:79], v[176:179], v[120:123], 0
	ds_read_b128 v[230:233], v196 offset:6656
	ds_read_b128 v[238:241], v196 offset:6688
	ds_read_b128 v[246:249], v196 offset:6720
	ds_read_b128 v[250:253], v196 offset:6752
	ds_read_b128 v[176:179], v196 offset:6784
	v_mfma_f32_32x32x16_bf16 v[64:79], v[172:175], v[124:127], v[64:79]
	ds_read_b128 v[172:175], v196 offset:6816
	s_nop 3
	v_max3_f32 v198, v80, v81, v82
	v_max3_f32 v199, v83, v84, v85
	v_max3_f32 v204, v86, v87, v88
	v_max3_f32 v205, v89, v90, v91
	v_max3_f32 v234, v92, v93, v94
	v_max3_f32 v199, v198, v199, v204
	v_max3_f32 v205, v205, v234, v95
	v_max3_f32 v204, v199, v205, v198
	v_mfma_f32_32x32x16_bf16 v[64:79], v[168:171], v[128:131], v[64:79]
	v_sub_f32_e32 v235, v204, v211
	v_cmp_lt_f32_e32 vcc, s81, v235
	s_or_b32 s8, vcc_lo, vcc_hi
	s_mov_b32 s9, s8
	s_or_b64 s[8:9], s[8:9], s[16:17]
	s_cbranch_scc1 .Lp4_rare_00

; template <int DQ, bool BIAS, bool TAIL>
; __device__ __forceinline__ void attn_item(const AttnItem& A, LAS unsigned char* lds, int wave_s_) {
;     ...
;                 s[0] = MFMA32(kf[0], qf[0][0], zero16v); s[1] = MFMA32(kf[0], qf[1][0], zero16v);
; #pragma unroll
;                 for (int kk = 1; kk < NKK; ++kk) { s[0] = MFMA32(kf[kk], qf[0][kk], s[0]); s[1] = MFMA32(kf[kk], qf[1][kk], s[1]); }
;                 s16x4 vlo[2][2], vhi[2][2];
; #pragma unroll
;                 for (int st = 0; st < 2; ++st)
; #pragma unroll
;                     for (int d = 0; d < 2; ++d) { const LAS unsigned char* vp = vb + ((32 * kbk + 16 * st) * VROW + 32 * d) * 2; vlo[st][d] = vtr(vp); vhi[st][d] = vtr(vp + 8 * VROW * 2); }
;                 __builtin_amdgcn_sched_barrier(0);
;                 float mx[2];
; #pragma unroll
;                 for (int qb = 0; qb < 2; ++qb) {
;                     if (BIAS || TAIL) {
;                         const int qk = A.q_kidx0 + 64 * w + 32 * qb + r32;
; #pragma unroll
;                         for (int i = 0; i < 16; ++i) { const int kidx = 64 * t + 32 * kbk + crow(i, hi);
;                             float v = s[qb][i]; if (BIAS) v += lut[kidx - qk + LUT0]; if (TAIL && kidx >= A.nkeys) v = -1.0e30f; s[qb][i] = v; }
;                     }
;                     const float t0 = max3f(s[qb][0], s[qb][1], s[qb][2]), t1 = max3f(s[qb][3], s[qb][4], s[qb][5]), t2 = max3f(s[qb][6], s[qb][7], s[qb][8]),
;                                 t3 = max3f(s[qb][9], s[qb][10], s[qb][11]), t4 = max3f(s[qb][12], s[qb][13], s[qb][14]);
;                     const float m = max3f(max3f(t0, t1, t2), max3f(t3, t4, s[qb][15]), t0);
;                     mx[qb] = swapmax(m, hi) - mref[qb];
;                 }
;                 const bool need0 = first || mx[0] > RESCALE_THR, need1 = first || mx[1] > RESCALE_THR;
;                 if (__builtin_amdgcn_ballot_w64(need0 || need1) != 0ull) {
; #pragma unroll
;                     for (int qb = 0; qb < 2; ++qb) {
;                         const float delta = (qb == 0 ? need0 : need1) ? mx[qb] : 0.f, alpha = __builtin_amdgcn_exp2f(-delta);
; #pragma unroll
;                         for (int i = 0; i < 16; ++i) { o[0][qb][i] *= alpha; o[1][qb][i] *= alpha; }
;                         lrun[qb] *= alpha; mref[qb] += delta;
;                     }
;                     first = false;
;                 }
.Lp6_body:
	s_mul_i32 s8, s21, 0x2400
	v_add_u32_e32 v229, s8, v227
	s_waitcnt lgkmcnt(5)
	v_mfma_f32_32x32x16_bf16 v[80:95], v[176:179], v[96:99], 0
	ds_read_b64_tr_b16 v[192:193], v229 offset:26624
	ds_read_b64_tr_b16 v[194:195], v229 offset:27776
	ds_read_b64_tr_b16 v[188:189], v229 offset:26688
	ds_read_b64_tr_b16 v[190:191], v229 offset:27840
	ds_read_b64_tr_b16 v[184:185], v229 offset:28928
	ds_read_b64_tr_b16 v[186:187], v229 offset:30080
	ds_read_b64_tr_b16 v[180:181], v229 offset:28992
	ds_read_b64_tr_b16 v[182:183], v229 offset:30144
	s_waitcnt lgkmcnt(12)
	v_mfma_f32_32x32x16_bf16 v[80:95], v[172:175], v[100:103], v[80:95]
	s_waitcnt lgkmcnt(11)
	v_mfma_f32_32x32x16_bf16 v[80:95], v[168:171], v[104:107], v[80:95]
	s_waitcnt lgkmcnt(10)
	v_mfma_f32_32x32x16_bf16 v[80:95], v[164:167], v[108:111], v[80:95]
	s_waitcnt lgkmcnt(9)
	v_mfma_f32_32x32x16_bf16 v[80:95], v[160:163], v[112:115], v[80:95]
	s_waitcnt lgkmcnt(8)
	v_mfma_f32_32x32x16_bf16 v[80:95], v[156:159], v[116:119], v[80:95]
	v_mfma_f32_32x32x16_bf16 v[64:79], v[176:179], v[120:123], 0
	ds_read_b128 v[230:233], v196 offset:6656
	ds_read_b128 v[238:241], v196 offset:6688
	ds_read_b128 v[246:249], v196 offset:6720
	ds_read_b128 v[250:253], v196 offset:6752
	ds_read_b128 v[176:179], v196 offset:6784
	v_mfma_f32_32x32x16_bf16 v[64:79], v[172:175], v[124:127], v[64:79]
	ds_read_b128 v[172:175], v196 offset:6816
	s_nop 3
	v_sub_f32_e32 v80, v80, v211
	v_sub_f32_e32 v81, v81, v211
	v_sub_f32_e32 v82, v82, v211
	v_sub_f32_e32 v83, v83, v211
	v_exp_f32_e32 v80, v80
	v_exp_f32_e32 v81, v81
	v_exp_f32_e32 v82, v82
	v_exp_f32_e32 v83, v83
	v_mfma_f32_32x32x16_bf16 v[64:79], v[168:171], v[128:131], v[64:79]
	v_sub_f32_e32 v84, v84, v211
	v_sub_f32_e32 v85, v85, v211
	v_sub_f32_e32 v86, v86, v211
	v_sub_f32_e32 v87, v87, v211
	v_exp_f32_e32 v84, v84
	v_exp_f32_e32 v85, v85
	v_exp_f32_e32 v86, v86
	v_exp_f32_e32 v87, v87
	v_add_f32_e32 v198, v80, v84
	v_add_f32_e32 v199, v81, v85
	v_add_f32_e32 v204, v82, v86
	v_add_f32_e32 v205, v83, v87
	v_mfma_f32_32x32x16_bf16 v[64:79], v[164:167], v[132:135], v[64:79]
	v_sub_f32_e32 v88, v88, v211
	v_sub_f32_e32 v89, v89, v211
	v_sub_f32_e32 v90, v90, v211
	v_sub_f32_e32 v91, v91, v211
	v_exp_f32_e32 v88, v88
	v_exp_f32_e32 v89, v89
	v_exp_f32_e32 v90, v90
	v_exp_f32_e32 v91, v91
	v_add_f32_e32 v198, v198, v88
	v_add_f32_e32 v199, v199, v89
	v_add_f32_e32 v204, v204, v90
	v_add_f32_e32 v205, v205, v91
	v_mfma_f32_32x32x16_bf16 v[64:79], v[160:163], v[140:143], v[64:79]
	v_sub_f32_e32 v92, v92, v211
	v_sub_f32_e32 v93, v93, v211
	v_sub_f32_e32 v94, v94, v211
	v_sub_f32_e32 v95, v95, v211
	v_exp_f32_e32 v92, v92
	v_exp_f32_e32 v93, v93
	v_exp_f32_e32 v94, v94
	v_exp_f32_e32 v95, v95
	v_add_f32_e32 v198, v198, v92
	v_add_f32_e32 v199, v199, v93
	v_add_f32_e32 v204, v204, v94
	v_add_f32_e32 v205, v205, v95
	v_mfma_f32_32x32x16_bf16 v[64:79], v[156:159], v[136:139], v[64:79]
	v_add_f32_e32 v198, v198, v199
	v_add_f32_e32 v204, v204, v205
	v_add_f32_e32 v198, v198, v204
	v_cmp_lt_f32_e32 vcc, 0x44800000, v198
	s_or_b32 s8, vcc_lo, vcc_hi
	s_mov_b32 s9, s8
	s_cbranch_scc1 .Lp6_rare_00
.Lp6_back_00:
	v_cvt_pk_bf16_f32 v80, v80, v81
	v_cvt_pk_bf16_f32 v81, v82, v83
	v_cvt_pk_bf16_f32 v82, v84, v85
	v_cvt_pk_bf16_f32 v83, v86, v87
	v_add_f32_e32 v212, v212, v198
	v_cvt_pk_bf16_f32 v84, v88, v89
	v_cvt_pk_bf16_f32 v85, v90, v91
	v_cvt_pk_bf16_f32 v86, v92, v93
	v_cvt_pk_bf16_f32 v87, v94, v95
	v_sub_f32_e32 v64, v64, v223
	v_sub_f32_e32 v65, v65, v223
	v_sub_f32_e32 v66, v66, v223
	s_waitcnt lgkmcnt(12)
	v_mfma_f32_32x32x16_bf16 v[48:63], v[192:195], v[80:83], v[48:63]
	v_sub_f32_e32 v67, v67, v223
	v_exp_f32_e32 v64, v64
	s_waitcnt lgkmcnt(10)
	v_mfma_f32_32x32x16_bf16 v[32:47], v[188:191], v[80:83], v[32:47]
	v_exp_f32_e32 v65, v65
	v_exp_f32_e32 v66, v66
	s_waitcnt lgkmcnt(8)
	v_mfma_f32_32x32x16_bf16 v[48:63], v[184:187], v[84:87], v[48:63]
	v_exp_f32_e32 v67, v67
	v_sub_f32_e32 v68, v68, v223
	s_waitcnt lgkmcnt(6)
	v_mfma_f32_32x32x16_bf16 v[32:47], v[180:183], v[84:87], v[32:47]
	v_sub_f32_e32 v69, v69, v223
	v_sub_f32_e32 v70, v70, v223
	v_sub_f32_e32 v71, v71, v223
	v_exp_f32_e32 v68, v68
	s_waitcnt lgkmcnt(5)
	v_mfma_f32_32x32x16_bf16 v[80:95], v[230:233], v[96:99], 0
	v_exp_f32_e32 v69, v69
	v_exp_f32_e32 v70, v70
	v_exp_f32_e32 v71, v71
	v_add_f32_e32 v198, v64, v68
	v_add_f32_e32 v199, v65, v69
	v_add_f32_e32 v204, v66, v70
	s_waitcnt lgkmcnt(4)
	v_mfma_f32_32x32x16_bf16 v[80:95], v[238:241], v[100:103], v[80:95]
	v_add_f32_e32 v205, v67, v71
	v_sub_f32_e32 v72, v72, v223
	v_sub_f32_e32 v73, v73, v223
	v_sub_f32_e32 v74, v74, v223
	v_sub_f32_e32 v75, v75, v223
	v_exp_f32_e32 v72, v72
	s_waitcnt lgkmcnt(3)
	v_mfma_f32_32x32x16_bf16 v[80:95], v[246:249], v[104:107], v[80:95]
	v_exp_f32_e32 v73, v73
	v_exp_f32_e32 v74, v74
	v_exp_f32_e32 v75, v75
	v_add_f32_e32 v198, v198, v72
	v_add_f32_e32 v199, v199, v73
	v_add_f32_e32 v204, v204, v74
	s_waitcnt lgkmcnt(2)
	v_mfma_f32_32x32x16_bf16 v[80:95], v[250:253], v[108:111], v[80:95]
	v_add_f32_e32 v205, v205, v75
	v_sub_f32_e32 v76, v76, v223
	v_sub_f32_e32 v77, v77, v223
	v_sub_f32_e32 v78, v78, v223
	v_sub_f32_e32 v79, v79, v223
	v_exp_f32_e32 v76, v76
	s_waitcnt lgkmcnt(1)
	v_mfma_f32_32x32x16_bf16 v[80:95], v[176:179], v[112:115], v[80:95]
	v_exp_f32_e32 v77, v77
	v_exp_f32_e32 v78, v78
	v_exp_f32_e32 v79, v79
	v_add_f32_e32 v198, v198, v76
	v_add_f32_e32 v199, v199, v77
	v_add_f32_e32 v204, v204, v78
	s_waitcnt lgkmcnt(0)
	v_mfma_f32_32x32x16_bf16 v[80:95], v[172:175], v[116:119], v[80:95]
	v_add_f32_e32 v205, v205, v79
	v_add_f32_e32 v198, v198, v199
	v_add_f32_e32 v204, v204, v205
	v_add_f32_e32 v198, v198, v204
	v_cmp_lt_f32_e32 vcc, 0x44800000, v198
	s_or_b32 s8, vcc_lo, vcc_hi
	s_mov_b32 s9, s8
	s_cbranch_scc1 .Lp6_rare_01
; template <int DQ, bool BIAS, bool TAIL>
; __device__ __forceinline__ void attn_item(const AttnItem& A, LAS unsigned char* lds, int wave_s_) {
;     ...
;                 s[0] = MFMA32(kf[0], qf[0][0], zero16v); s[1] = MFMA32(kf[0], qf[1][0], zero16v);
; #pragma unroll
;                 for (int kk = 1; kk < NKK; ++kk) { s[0] = MFMA32(kf[kk], qf[0][kk], s[0]); s[1] = MFMA32(kf[kk], qf[1][kk], s[1]); }
;                 s16x4 vlo[2][2], vhi[2][2];
; #pragma unroll
;                 for (int st = 0; st < 2; ++st)
; #pragma unroll
;                     for (int d = 0; d < 2; ++d) { const LAS unsigned char* vp = vb + ((32 * kbk + 16 * st) * VROW + 32 * d) * 2; vlo[st][d] = vtr(vp); vhi[st][d] = vtr(vp + 8 * VROW * 2); }
;                 __builtin_amdgcn_sched_barrier(0);
;                 float mx[2];
; #pragma unroll
;                 for (int qb = 0; qb < 2; ++qb) {
;                     if (BIAS || TAIL) {
;                         const int qk = A.q_kidx0 + 64 * w + 32 * qb + r32;
; #pragma unroll
;                         for (int i = 0; i < 16; ++i) { const int kidx = 64 * t + 32 * kbk + crow(i, hi);
;                             float v = s[qb][i]; if (BIAS) v += lut[kidx - qk + LUT0]; if (TAIL && kidx >= A.nkeys) v = -1.0e30f; s[qb][i] = v; }
;                     }
;                     const float t0 = max3f(s[qb][0], s[qb][1], s[qb][2]), t1 = max3f(s[qb][3], s[qb][4], s[qb][5]), t2 = max3f(s[qb][6], s[qb][7], s[qb][8]),
;                                 t3 = max3f(s[qb][9], s[qb][10], s[qb][11]), t4 = max3f(s[qb][12], s[qb][13], s[qb][14]);
;                     const float m = max3f(max3f(t0, t1, t2), max3f(t3, t4, s[qb][15]), t0);
;                     mx[qb] = swapmax(m, hi) - mref[qb];
;                 }
;                 const bool need0 = first || mx[0] > RESCALE_THR, need1 = first || mx[1] > RESCALE_THR;
;                 if (__builtin_amdgcn_ballot_w64(need0 || need1) != 0ull) {
; #pragma unroll
;                     for (int qb = 0; qb < 2; ++qb) {
;                         const float delta = (qb == 0 ? need0 : need1) ? mx[qb] : 0.f, alpha = __builtin_amdgcn_exp2f(-delta);
; #pragma unroll
;                         for (int i = 0; i < 16; ++i) { o[0][qb][i] *= alpha; o[1][qb][i] *= alpha; }
;                         lrun[qb] *= alpha; mref[qb] += delta;
;                     }
;                     first = false;
;                 }
.Lp6_back_01:
	v_cvt_pk_bf16_f32 v64, v64, v65
	v_cvt_pk_bf16_f32 v65, v66, v67
	v_cvt_pk_bf16_f32 v66, v68, v69
	v_cvt_pk_bf16_f32 v67, v70, v71
	v_add_f32_e32 v213, v213, v198
	v_cvt_pk_bf16_f32 v68, v72, v73
	v_cvt_pk_bf16_f32 v69, v74, v75
	v_cvt_pk_bf16_f32 v70, v76, v77
	v_cvt_pk_bf16_f32 v71, v78, v79
	v_sub_f32_e32 v80, v80, v211
	v_sub_f32_e32 v81, v81, v211
	v_sub_f32_e32 v82, v82, v211
	v_mfma_f32_32x32x16_bf16 v[16:31], v[192:195], v[64:67], v[16:31]
	v_sub_f32_e32 v83, v83, v211
	v_exp_f32_e32 v80, v80
	v_mfma_f32_32x32x16_bf16 v[0:15], v[188:191], v[64:67], v[0:15]
	v_exp_f32_e32 v81, v81
	v_exp_f32_e32 v82, v82
	v_mfma_f32_32x32x16_bf16 v[16:31], v[184:187], v[68:71], v[16:31]
	v_exp_f32_e32 v83, v83
	v_sub_f32_e32 v84, v84, v211
	v_mfma_f32_32x32x16_bf16 v[0:15], v[180:183], v[68:71], v[0:15]
	ds_read_b64_tr_b16 v[192:193], v229 offset:31232
	ds_read_b64_tr_b16 v[194:195], v229 offset:32384
	ds_read_b64_tr_b16 v[188:189], v229 offset:31296
	ds_read_b64_tr_b16 v[190:191], v229 offset:32448
	ds_read_b64_tr_b16 v[184:185], v229 offset:33536
	ds_read_b64_tr_b16 v[186:187], v229 offset:34688
	ds_read_b64_tr_b16 v[180:181], v229 offset:33600
	ds_read_b64_tr_b16 v[182:183], v229 offset:34752
	v_sub_f32_e32 v85, v85, v211
	v_sub_f32_e32 v86, v86, v211
	v_sub_f32_e32 v87, v87, v211
	v_exp_f32_e32 v84, v84
	v_mfma_f32_32x32x16_bf16 v[64:79], v[230:233], v[120:123], 0
	v_exp_f32_e32 v85, v85
	v_exp_f32_e32 v86, v86
	v_exp_f32_e32 v87, v87
	v_add_f32_e32 v198, v80, v84
	v_add_f32_e32 v199, v81, v85
	v_add_f32_e32 v204, v82, v86
	v_mfma_f32_32x32x16_bf16 v[64:79], v[238:241], v[124:127], v[64:79]
	v_add_f32_e32 v205, v83, v87
	v_sub_f32_e32 v88, v88, v211
	v_sub_f32_e32 v89, v89, v211
	v_sub_f32_e32 v90, v90, v211
	v_sub_f32_e32 v91, v91, v211
	v_exp_f32_e32 v88, v88
	v_mfma_f32_32x32x16_bf16 v[64:79], v[246:249], v[128:131], v[64:79]
	v_exp_f32_e32 v89, v89
	v_exp_f32_e32 v90, v90
	v_exp_f32_e32 v91, v91
	v_add_f32_e32 v198, v198, v88
	v_add_f32_e32 v199, v199, v89
	v_add_f32_e32 v204, v204, v90
	v_mfma_f32_32x32x16_bf16 v[64:79], v[250:253], v[132:135], v[64:79]
	v_add_f32_e32 v205, v205, v91
	v_sub_f32_e32 v92, v92, v211
	v_sub_f32_e32 v93, v93, v211
	v_sub_f32_e32 v94, v94, v211
	v_sub_f32_e32 v95, v95, v211
	v_exp_f32_e32 v92, v92
	v_mfma_f32_32x32x16_bf16 v[64:79], v[176:179], v[140:143], v[64:79]
	v_exp_f32_e32 v93, v93
	v_exp_f32_e32 v94, v94
	v_exp_f32_e32 v95, v95
	v_add_f32_e32 v198, v198, v92
	v_add_f32_e32 v199, v199, v93
	v_add_f32_e32 v204, v204, v94
	v_mfma_f32_32x32x16_bf16 v[64:79], v[172:175], v[136:139], v[64:79]
	v_add_f32_e32 v205, v205, v95
	v_add_f32_e32 v198, v198, v199
	v_add_f32_e32 v204, v204, v205
	v_add_f32_e32 v198, v198, v204
	v_cmp_lt_f32_e32 vcc, 0x44800000, v198
	s_or_b32 s8, vcc_lo, vcc_hi
	s_mov_b32 s9, s8
	s_cbranch_scc1 .Lp6_rare_10
.Lp6_back_10:
	v_cvt_pk_bf16_f32 v80, v80, v81
	v_cvt_pk_bf16_f32 v81, v82, v83
	v_cvt_pk_bf16_f32 v82, v84, v85
	v_cvt_pk_bf16_f32 v83, v86, v87
	v_add_f32_e32 v212, v212, v198
	v_cvt_pk_bf16_f32 v84, v88, v89
	v_cvt_pk_bf16_f32 v85, v90, v91
	v_cvt_pk_bf16_f32 v86, v92, v93
	v_cvt_pk_bf16_f32 v87, v94, v95
	v_sub_f32_e32 v64, v64, v223
	v_sub_f32_e32 v65, v65, v223
	v_sub_f32_e32 v66, v66, v223
	v_sub_f32_e32 v67, v67, v223
	v_exp_f32_e32 v64, v64
	v_exp_f32_e32 v65, v65
	v_exp_f32_e32 v66, v66
	v_exp_f32_e32 v67, v67
	v_sub_f32_e32 v68, v68, v223
	v_sub_f32_e32 v69, v69, v223
	s_waitcnt lgkmcnt(6)
	v_mfma_f32_32x32x16_bf16 v[48:63], v[192:195], v[80:83], v[48:63]
	v_sub_f32_e32 v70, v70, v223
	v_sub_f32_e32 v71, v71, v223
	v_exp_f32_e32 v68, v68
	v_exp_f32_e32 v69, v69
	v_exp_f32_e32 v70, v70
	v_exp_f32_e32 v71, v71
	v_add_f32_e32 v198, v64, v68
	v_add_f32_e32 v199, v65, v69
	v_add_f32_e32 v204, v66, v70
	v_add_f32_e32 v205, v67, v71
	v_sub_f32_e32 v72, v72, v223
	v_sub_f32_e32 v73, v73, v223
	s_waitcnt lgkmcnt(4)
	v_mfma_f32_32x32x16_bf16 v[32:47], v[188:191], v[80:83], v[32:47]
	v_sub_f32_e32 v74, v74, v223
	v_sub_f32_e32 v75, v75, v223
	v_exp_f32_e32 v72, v72
	v_exp_f32_e32 v73, v73
	v_exp_f32_e32 v74, v74
	v_exp_f32_e32 v75, v75
	v_add_f32_e32 v198, v198, v72
	v_add_f32_e32 v199, v199, v73
	v_add_f32_e32 v204, v204, v74
	v_add_f32_e32 v205, v205, v75
	v_sub_f32_e32 v76, v76, v223
	v_sub_f32_e32 v77, v77, v223
	s_waitcnt lgkmcnt(2)
	v_mfma_f32_32x32x16_bf16 v[48:63], v[184:187], v[84:87], v[48:63]
	v_sub_f32_e32 v78, v78, v223
	v_sub_f32_e32 v79, v79, v223
	v_exp_f32_e32 v76, v76
	v_exp_f32_e32 v77, v77
	v_exp_f32_e32 v78, v78
	v_exp_f32_e32 v79, v79
	v_add_f32_e32 v198, v198, v76
	v_add_f32_e32 v199, v199, v77
	v_add_f32_e32 v204, v204, v78
	v_add_f32_e32 v205, v205, v79
	v_add_f32_e32 v198, v198, v199
	v_add_f32_e32 v204, v204, v205
	s_waitcnt lgkmcnt(0)
	v_mfma_f32_32x32x16_bf16 v[32:47], v[180:183], v[84:87], v[32:47]
	v_add_f32_e32 v198, v198, v204
	v_cmp_lt_f32_e32 vcc, 0x44800000, v198
	s_or_b32 s8, vcc_lo, vcc_hi
	s_mov_b32 s9, s8
	s_cbranch_scc1 .Lp6_rare_11
; #define MFMA32(a, b, c) __builtin_amdgcn_mfma_f32_32x32x16_bf16((a), (b), (c), 0, 0, 0)
; template <int DQ, bool BIAS, bool TAIL>
; __device__ __forceinline__ void attn_item(const AttnItem& A, LAS unsigned char* lds, int wave_s_) {
;     ...
;                 const bool need0 = first || mx[0] > RESCALE_THR, need1 = first || mx[1] > RESCALE_THR;
;                 if (__builtin_amdgcn_ballot_w64(need0 || need1) != 0ull) {
; #pragma unroll
;                     for (int qb = 0; qb < 2; ++qb) {
;                         const float delta = (qb == 0 ? need0 : need1) ? mx[qb] : 0.f, alpha = __builtin_amdgcn_exp2f(-delta);
; #pragma unroll
;                         for (int i = 0; i < 16; ++i) { o[0][qb][i] *= alpha; o[1][qb][i] *= alpha; }
;                         lrun[qb] *= alpha; mref[qb] += delta;
;                     }
;                     first = false;
;                 }
;     ...
;                 for (int st = 0; st < 2; ++st)
; #pragma unroll
;                     for (int d = 0; d < 2; ++d) {
;                         const bf16x8 vf = __builtin_shufflevector(vlo[st][d], vhi[st][d], 0, 1, 2, 3, 4, 5, 6, 7);
;                         o[d][0] = MFMA32(vf, pf[st][0], o[d][0]);
;                         o[d][1] = MFMA32(vf, pf[st][1], o[d][1]);
;                     }
.Lp6_back_11:
	v_cvt_pk_bf16_f32 v64, v64, v65
	v_cvt_pk_bf16_f32 v65, v66, v67
	v_cvt_pk_bf16_f32 v66, v68, v69
	v_cvt_pk_bf16_f32 v67, v70, v71
	v_add_f32_e32 v213, v213, v198
	v_cvt_pk_bf16_f32 v68, v72, v73
	v_cvt_pk_bf16_f32 v69, v74, v75
	v_cvt_pk_bf16_f32 v70, v76, v77
	v_cvt_pk_bf16_f32 v71, v78, v79
	s_nop 1
	v_mfma_f32_32x32x16_bf16 v[16:31], v[192:195], v[64:67], v[16:31]
	v_mfma_f32_32x32x16_bf16 v[0:15], v[188:191], v[64:67], v[0:15]
	v_mfma_f32_32x32x16_bf16 v[16:31], v[184:187], v[68:71], v[16:31]
	v_mfma_f32_32x32x16_bf16 v[0:15], v[180:183], v[68:71], v[0:15]
	s_branch .LBB0_1484
.Lp6_rare_00:
	s_nop 15
	v_max3_f32 v199, v80, v81, v82
	v_max3_f32 v204, v83, v84, v85
	v_max3_f32 v205, v86, v87, v88
	v_max3_f32 v234, v89, v90, v91
	v_max3_f32 v235, v92, v93, v94
	v_max3_f32 v199, v199, v204, v205
	v_max3_f32 v234, v234, v235, v95
	v_max_f32_e32 v199, v199, v234
	v_mov_b32_e32 v204, v199
	s_nop 1
	v_permlane32_swap_b32_e32 v204, v199
	s_nop 1
	v_max_f32_e32 v199, v204, v199
	v_frexp_exp_i32_f32_e32 v204, v199
	v_sub_u32_e32 v204, 0, v204
	v_cndmask_b32_e64 v204, 0, v204, s[8:9]
	v_cvt_f32_i32_e32 v205, v204
	v_sub_f32_e32 v211, v211, v205
	v_ldexp_f32 v80, v80, v204
	v_ldexp_f32 v81, v81, v204
	v_ldexp_f32 v82, v82, v204
	v_ldexp_f32 v83, v83, v204
	v_ldexp_f32 v84, v84, v204
	v_ldexp_f32 v85, v85, v204
	v_ldexp_f32 v86, v86, v204
	v_ldexp_f32 v87, v87, v204
	v_ldexp_f32 v88, v88, v204
	v_ldexp_f32 v89, v89, v204
	v_ldexp_f32 v90, v90, v204
	v_ldexp_f32 v91, v91, v204
	v_ldexp_f32 v92, v92, v204
	v_ldexp_f32 v93, v93, v204
	v_ldexp_f32 v94, v94, v204
	v_ldexp_f32 v95, v95, v204
	v_ldexp_f32 v198, v198, v204
	v_ldexp_f32 v212, v212, v204
	v_ldexp_f32 v32, v32, v204
	v_ldexp_f32 v33, v33, v204
	v_ldexp_f32 v34, v34, v204
	v_ldexp_f32 v35, v35, v204
	v_ldexp_f32 v36, v36, v204
	v_ldexp_f32 v37, v37, v204
	v_ldexp_f32 v38, v38, v204
	v_ldexp_f32 v39, v39, v204
	v_ldexp_f32 v40, v40, v204
	v_ldexp_f32 v41, v41, v204
	v_ldexp_f32 v42, v42, v204
	v_ldexp_f32 v43, v43, v204
	v_ldexp_f32 v44, v44, v204
	v_ldexp_f32 v45, v45, v204
	v_ldexp_f32 v46, v46, v204
	v_ldexp_f32 v47, v47, v204
	v_ldexp_f32 v48, v48, v204
	v_ldexp_f32 v49, v49, v204
	v_ldexp_f32 v50, v50, v204
	v_ldexp_f32 v51, v51, v204
	v_ldexp_f32 v52, v52, v204
	v_ldexp_f32 v53, v53, v204
	v_ldexp_f32 v54, v54, v204
	v_ldexp_f32 v55, v55, v204
	v_ldexp_f32 v56, v56, v204
	v_ldexp_f32 v57, v57, v204
	v_ldexp_f32 v58, v58, v204
	v_ldexp_f32 v59, v59, v204
	v_ldexp_f32 v60, v60, v204
	v_ldexp_f32 v61, v61, v204
	v_ldexp_f32 v62, v62, v204
	v_ldexp_f32 v63, v63, v204
	s_branch .Lp6_back_00
.Lp6_rare_01:
	s_nop 15
	v_max3_f32 v199, v64, v65, v66
	v_max3_f32 v204, v67, v68, v69
	v_max3_f32 v205, v70, v71, v72
	v_max3_f32 v234, v73, v74, v75
	v_max3_f32 v235, v76, v77, v78
	v_max3_f32 v199, v199, v204, v205
	v_max3_f32 v234, v234, v235, v79
	v_max_f32_e32 v199, v199, v234
	v_mov_b32_e32 v204, v199
	s_nop 1
	v_permlane32_swap_b32_e32 v204, v199
	s_nop 1
	v_max_f32_e32 v199, v204, v199
	v_frexp_exp_i32_f32_e32 v204, v199
	v_sub_u32_e32 v204, 0, v204
	v_cndmask_b32_e64 v204, 0, v204, s[8:9]
	v_cvt_f32_i32_e32 v205, v204
	v_sub_f32_e32 v223, v223, v205
	v_ldexp_f32 v64, v64, v204
	v_ldexp_f32 v65, v65, v204
	v_ldexp_f32 v66, v66, v204
	v_ldexp_f32 v67, v67, v204
	v_ldexp_f32 v68, v68, v204
	v_ldexp_f32 v69, v69, v204
	v_ldexp_f32 v70, v70, v204
	v_ldexp_f32 v71, v71, v204
	v_ldexp_f32 v72, v72, v204
	v_ldexp_f32 v73, v73, v204
	v_ldexp_f32 v74, v74, v204
	v_ldexp_f32 v75, v75, v204
	v_ldexp_f32 v76, v76, v204
	v_ldexp_f32 v77, v77, v204
	v_ldexp_f32 v78, v78, v204
	v_ldexp_f32 v79, v79, v204
	v_ldexp_f32 v198, v198, v204
	v_ldexp_f32 v213, v213, v204
	v_ldexp_f32 v0, v0, v204
	v_ldexp_f32 v1, v1, v204
	v_ldexp_f32 v2, v2, v204
	v_ldexp_f32 v3, v3, v204
	v_ldexp_f32 v4, v4, v204
	v_ldexp_f32 v5, v5, v204
	v_ldexp_f32 v6, v6, v204
	v_ldexp_f32 v7, v7, v204
	v_ldexp_f32 v8, v8, v204
	v_ldexp_f32 v9, v9, v204
	v_ldexp_f32 v10, v10, v204
	v_ldexp_f32 v11, v11, v204
	v_ldexp_f32 v12, v12, v204
	v_ldexp_f32 v13, v13, v204
	v_ldexp_f32 v14, v14, v204
	v_ldexp_f32 v15, v15, v204
	v_ldexp_f32 v16, v16, v204
	v_ldexp_f32 v17, v17, v204
	v_ldexp_f32 v18, v18, v204
	v_ldexp_f32 v19, v19, v204
	v_ldexp_f32 v20, v20, v204
	v_ldexp_f32 v21, v21, v204
	v_ldexp_f32 v22, v22, v204
	v_ldexp_f32 v23, v23, v204
	v_ldexp_f32 v24, v24, v204
	v_ldexp_f32 v25, v25, v204
	v_ldexp_f32 v26, v26, v204
	v_ldexp_f32 v27, v27, v204
	v_ldexp_f32 v28, v28, v204
	v_ldexp_f32 v29, v29, v204
	v_ldexp_f32 v30, v30, v204
	v_ldexp_f32 v31, v31, v204
	s_branch .Lp6_back_01
